# kt-MFMA version + nt (streaming) hints on weight-transpose loads and stores
# speedup vs baseline: 1.0158x; 1.0158x over previous
; #define LAS __attribute__((address_space(3)))
; DI u32x4 pack8(const float* f) { u32x4 w; w.x = pk2(f[0], f[1]); w.y = pk2(f[2], f[3]); w.z = pk2(f[4], f[5]); w.w = pk2(f[6], f[7]); return w; }
; template <int MODE> DI void transpose_job(LAS unsigned char* lds, const float* src, int K, int N, bf16_t* dst, int bid, int nblk) {
;     ...
;         for (int q = 0; q < 2; ++q) { const int t = t0 + q * nblk; LAS float* tl = (LAS float*)(lds + q * 16640);
;             if (t < ntile) { const int k0 = (t / tn) * 64, n0 = (t % tn) * 64, n = tid >> 3, ko = (tid & 7) * 8;
;                 if (n0 + n < N) { float f[8];
; #pragma unroll
;                     for (int jq = 0; jq < 8; ++jq) f[jq] = tl[(ko + jq) * 65 + n];
;                     *(u32x4*)(dst + (size_t)rowmap<MODE>(n0 + n) * K + k0 + ko) = pack8(f); } } }
.LBB0_174:
	s_waitcnt lgkmcnt(0)
	s_barrier
	v_add_u32_e32 v4, s20, v15
	s_movk_i32 s20, 0x800
	v_cmp_gt_i32_e32 vcc, s20, v4
	s_and_saveexec_b64 s[20:21], vcc
	s_cbranch_execz .LBB0_176
	v_add_u32_e32 v2, v16, v18
	ds_read2_b32 v[6:7], v2 offset1:65
	ds_read2_b32 v[8:9], v2 offset0:130 offset1:195
	v_add_u32_e32 v2, 0x400, v2
	ds_read2_b32 v[10:11], v2 offset0:4 offset1:69
	ds_read2_b32 v[20:21], v2 offset0:134 offset1:199
	s_ashr_i32 s26, s31, 5
	v_ashrrev_i32_e32 v5, 31, v4
	s_lshl_b32 s26, s26, 6
	v_lshlrev_b64 v[4:5], 11, v[4:5]
	v_lshl_add_u64 v[4:5], s[2:3], 0, v[4:5]
	s_ashr_i32 s27, s26, 31
	v_lshl_add_u64 v[4:5], s[26:27], 1, v[4:5]
	v_lshlrev_b32_e32 v2, 1, v12
	s_waitcnt lgkmcnt(3)
	v_cvt_pk_bf16_f32 v6, v6, v7
	s_waitcnt lgkmcnt(2)
	v_cvt_pk_bf16_f32 v7, v8, v9
	s_waitcnt lgkmcnt(1)
	v_cvt_pk_bf16_f32 v8, v10, v11
	s_waitcnt lgkmcnt(0)
	v_cvt_pk_bf16_f32 v9, v20, v21
	v_lshl_add_u64 v[4:5], v[4:5], 0, v[2:3]
	global_store_dwordx4 v[4:5], v[6:9], off nt
.LBB0_176:
	s_or_b64 exec, exec, s[20:21]
	s_andn2_b64 vcc, exec, s[22:23]
	s_cbranch_vccnz .LBB0_167
	s_ashr_i32 s20, s34, 31
	s_lshr_b32 s20, s20, 27
	s_add_i32 s22, s34, s20
	s_and_b32 s20, s22, 0x3ffffe0
	s_sub_i32 s20, s34, s20
	v_lshl_add_u32 v4, s20, 6, v15
	s_movk_i32 s20, 0x800
	v_cmp_gt_i32_e32 vcc, s20, v4
	s_and_saveexec_b64 s[20:21], vcc
	s_cbranch_execz .LBB0_166
	v_add_u32_e32 v2, v16, v18
	v_add_u32_e32 v5, 0x4000, v2
	ds_read2_b32 v[6:7], v5 offset0:64 offset1:129
	v_add_u32_e32 v5, 0x4200, v2
	ds_read2_b32 v[8:9], v5 offset0:66 offset1:131
	v_add_u32_e32 v5, 0x4400, v2
	v_add_u32_e32 v2, 0x4600, v2
	ds_read2_b32 v[10:11], v5 offset0:68 offset1:133
	ds_read2_b32 v[20:21], v2 offset0:70 offset1:135
	s_ashr_i32 s22, s22, 5
	v_ashrrev_i32_e32 v5, 31, v4
	s_lshl_b32 s22, s22, 6
	v_lshlrev_b64 v[4:5], 11, v[4:5]
	v_lshl_add_u64 v[4:5], s[2:3], 0, v[4:5]
	s_ashr_i32 s23, s22, 31
	v_lshl_add_u64 v[4:5], s[22:23], 1, v[4:5]
	v_lshlrev_b32_e32 v2, 1, v12
	s_waitcnt lgkmcnt(3)
	v_cvt_pk_bf16_f32 v6, v6, v7
	s_waitcnt lgkmcnt(2)
	v_cvt_pk_bf16_f32 v7, v8, v9
	s_waitcnt lgkmcnt(1)
	v_cvt_pk_bf16_f32 v8, v10, v11
	s_waitcnt lgkmcnt(0)
	v_cvt_pk_bf16_f32 v9, v20, v21
	v_lshl_add_u64 v[4:5], v[4:5], 0, v[2:3]
	global_store_dwordx4 v[4:5], v[6:9], off nt
	s_branch .LBB0_166

; #define LAS __attribute__((address_space(3)))
; DI u32x4 pack8(const float* f) { u32x4 w; w.x = pk2(f[0], f[1]); w.y = pk2(f[2], f[3]); w.z = pk2(f[4], f[5]); w.w = pk2(f[6], f[7]); return w; }
; template <int MODE> DI void transpose_job(LAS unsigned char* lds, const float* src, int K, int N, bf16_t* dst, int bid, int nblk) {
;     ...
;         for (int q = 0; q < 2; ++q) { const int t = t0 + q * nblk; LAS float* tl = (LAS float*)(lds + q * 16640);
;             if (t < ntile) { const int k0 = (t / tn) * 64, n0 = (t % tn) * 64, n = tid >> 3, ko = (tid & 7) * 8;
;                 if (n0 + n < N) { float f[8];
; #pragma unroll
;                     for (int jq = 0; jq < 8; ++jq) f[jq] = tl[(ko + jq) * 65 + n];
;                     *(u32x4*)(dst + (size_t)rowmap<MODE>(n0 + n) * K + k0 + ko) = pack8(f); } } }
.LBB0_189:
	s_waitcnt lgkmcnt(0)
	s_barrier
	v_add_u32_e32 v4, s20, v15
	s_movk_i32 s20, 0x800
	v_cmp_gt_i32_e32 vcc, s20, v4
	s_and_saveexec_b64 s[20:21], vcc
	s_cbranch_execz .LBB0_191
	v_add_u32_e32 v2, v16, v18
	ds_read2_b32 v[6:7], v2 offset1:65
	ds_read2_b32 v[8:9], v2 offset0:130 offset1:195
	v_add_u32_e32 v2, 0x400, v2
	ds_read2_b32 v[10:11], v2 offset0:4 offset1:69
	ds_read2_b32 v[20:21], v2 offset0:134 offset1:199
	s_ashr_i32 s26, s31, 5
	v_ashrrev_i32_e32 v5, 31, v4
	s_lshl_b32 s26, s26, 6
	v_lshlrev_b64 v[4:5], 12, v[4:5]
	v_lshl_add_u64 v[4:5], s[2:3], 0, v[4:5]
	s_ashr_i32 s27, s26, 31
	v_lshl_add_u64 v[4:5], s[26:27], 1, v[4:5]
	v_lshlrev_b32_e32 v2, 1, v12
	s_waitcnt lgkmcnt(3)
	v_cvt_pk_bf16_f32 v6, v6, v7
	s_waitcnt lgkmcnt(2)
	v_cvt_pk_bf16_f32 v7, v8, v9
	s_waitcnt lgkmcnt(1)
	v_cvt_pk_bf16_f32 v8, v10, v11
	s_waitcnt lgkmcnt(0)
	v_cvt_pk_bf16_f32 v9, v20, v21
	v_lshl_add_u64 v[4:5], v[4:5], 0, v[2:3]
	global_store_dwordx4 v[4:5], v[6:9], off nt
.LBB0_191:
	s_or_b64 exec, exec, s[20:21]
	s_andn2_b64 vcc, exec, s[22:23]
	s_cbranch_vccnz .LBB0_182
	s_ashr_i32 s20, s34, 31
	s_lshr_b32 s20, s20, 27
	s_add_i32 s22, s34, s20
	s_and_b32 s20, s22, 0x3ffffe0
	s_sub_i32 s20, s34, s20
	v_lshl_add_u32 v4, s20, 6, v15
	s_movk_i32 s20, 0x800
	v_cmp_gt_i32_e32 vcc, s20, v4
	s_and_saveexec_b64 s[20:21], vcc
	s_cbranch_execz .LBB0_181
	v_add_u32_e32 v2, v16, v18
	v_add_u32_e32 v5, 0x4000, v2
	ds_read2_b32 v[6:7], v5 offset0:64 offset1:129
	v_add_u32_e32 v5, 0x4200, v2
	ds_read2_b32 v[8:9], v5 offset0:66 offset1:131
	v_add_u32_e32 v5, 0x4400, v2
	v_add_u32_e32 v2, 0x4600, v2
	ds_read2_b32 v[10:11], v5 offset0:68 offset1:133
	ds_read2_b32 v[20:21], v2 offset0:70 offset1:135
	s_ashr_i32 s22, s22, 5
	v_ashrrev_i32_e32 v5, 31, v4
	s_lshl_b32 s22, s22, 6
	v_lshlrev_b64 v[4:5], 12, v[4:5]
	v_lshl_add_u64 v[4:5], s[2:3], 0, v[4:5]
	s_ashr_i32 s23, s22, 31
	v_lshl_add_u64 v[4:5], s[22:23], 1, v[4:5]
	v_lshlrev_b32_e32 v2, 1, v12
	s_waitcnt lgkmcnt(3)
	v_cvt_pk_bf16_f32 v6, v6, v7
	s_waitcnt lgkmcnt(2)
	v_cvt_pk_bf16_f32 v7, v8, v9
	s_waitcnt lgkmcnt(1)
	v_cvt_pk_bf16_f32 v8, v10, v11
	s_waitcnt lgkmcnt(0)
	v_cvt_pk_bf16_f32 v9, v20, v21
	v_lshl_add_u64 v[4:5], v[4:5], 0, v[2:3]
	global_store_dwordx4 v[4:5], v[6:9], off nt
	s_branch .LBB0_181

; DI u32x4 pack8(const float* f) { u32x4 w; w.x = pk2(f[0], f[1]); w.y = pk2(f[2], f[3]); w.z = pk2(f[4], f[5]); w.w = pk2(f[6], f[7]); return w; }
; template <int MODE> DI void transpose_job(LAS unsigned char* lds, const float* src, int K, int N, bf16_t* dst, int bid, int nblk) {
;     ...
;             if (t < ntile) { const int k0 = (t / tn) * 64, n0 = (t % tn) * 64, n = tid >> 3, ko = (tid & 7) * 8;
;                 if (n0 + n < N) { float f[8];
; #pragma unroll
;                     for (int jq = 0; jq < 8; ++jq) f[jq] = tl[(ko + jq) * 65 + n];
;                     *(u32x4*)(dst + (size_t)rowmap<MODE>(n0 + n) * K + k0 + ko) = pack8(f); } } }
.LBB0_196:
	s_or_b64 exec, exec, s[22:23]
	v_ashrrev_i32_e32 v15, 31, v14
	s_waitcnt lgkmcnt(3)
	v_cvt_pk_bf16_f32 v6, v6, v7
	s_waitcnt lgkmcnt(2)
	v_cvt_pk_bf16_f32 v7, v8, v9
	s_waitcnt lgkmcnt(1)
	v_cvt_pk_bf16_f32 v8, v10, v11
	s_lshl_b32 s22, s26, 6
	v_lshlrev_b64 v[10:11], 12, v[14:15]
	v_lshl_add_u64 v[10:11], s[2:3], 0, v[10:11]
	s_ashr_i32 s23, s22, 31
	v_lshl_add_u64 v[10:11], s[22:23], 1, v[10:11]
	v_lshlrev_b32_e32 v2, 1, v4
	s_waitcnt lgkmcnt(0)
	v_cvt_pk_bf16_f32 v9, v12, v13
	v_lshl_add_u64 v[10:11], v[10:11], 0, v[2:3]
	global_store_dwordx4 v[10:11], v[6:9], off nt

; DI u32x4 pack8(const float* f) { u32x4 w; w.x = pk2(f[0], f[1]); w.y = pk2(f[2], f[3]); w.z = pk2(f[4], f[5]); w.w = pk2(f[6], f[7]); return w; }
; template <int MODE> DI void transpose_job(LAS unsigned char* lds, const float* src, int K, int N, bf16_t* dst, int bid, int nblk) {
;     ...
;             if (t < ntile) { const int k0 = (t / tn) * 64, n0 = (t % tn) * 64, n = tid >> 3, ko = (tid & 7) * 8;
;                 if (n0 + n < N) { float f[8];
; #pragma unroll
;                     for (int jq = 0; jq < 8; ++jq) f[jq] = tl[(ko + jq) * 65 + n];
;                     *(u32x4*)(dst + (size_t)rowmap<MODE>(n0 + n) * K + k0 + ko) = pack8(f); } } }
.LBB0_201:
	s_waitcnt lgkmcnt(0)
	s_barrier
	v_add_u32_e32 v14, s26, v16
	s_movk_i32 s21, 0x2c00
	v_cmp_gt_i32_e32 vcc, s21, v14
	s_and_saveexec_b64 s[26:27], vcc
	s_cbranch_execz .LBB0_207
	v_add_u32_e32 v2, v17, v19
	ds_read2_b32 v[6:7], v2 offset1:65
	ds_read2_b32 v[8:9], v2 offset0:130 offset1:195
	v_add_u32_e32 v2, 0x400, v2
	ds_read2_b32 v[10:11], v2 offset0:4 offset1:69
	ds_read2_b32 v[12:13], v2 offset0:134 offset1:199
	s_movk_i32 s21, 0x15ff
	v_cmp_lt_i32_e32 vcc, s21, v14
	v_lshlrev_b32_e32 v2, 1, v14
	v_and_b32_e32 v15, 0x7f, v14
	s_and_saveexec_b64 s[28:29], vcc
	s_xor_b64 s[28:29], exec, s[28:29]
	v_add_u32_e32 v2, 0x7fffd400, v2
	v_and_b32_e32 v2, 0x7fffff00, v2
	v_or3_b32 v14, v15, v2, s6
	s_andn2_saveexec_b64 s[28:29], s[28:29]
	s_movk_i32 s21, 0xff00
	v_and_or_b32 v14, v2, s21, v15
	s_or_b64 exec, exec, s[28:29]
	v_ashrrev_i32_e32 v15, 31, v14
	s_waitcnt lgkmcnt(3)
	v_cvt_pk_bf16_f32 v6, v6, v7
	s_waitcnt lgkmcnt(2)
	v_cvt_pk_bf16_f32 v7, v8, v9
	s_waitcnt lgkmcnt(1)
	v_cvt_pk_bf16_f32 v8, v10, v11
	v_lshlrev_b64 v[10:11], 12, v[14:15]
	v_lshl_add_u64 v[10:11], s[2:3], 0, v[10:11]
	s_ashr_i32 s21, s20, 31
	v_lshl_add_u64 v[10:11], s[20:21], 1, v[10:11]
	v_lshlrev_b32_e32 v2, 1, v4
	s_waitcnt lgkmcnt(0)
	v_cvt_pk_bf16_f32 v9, v12, v13
	v_lshl_add_u64 v[10:11], v[10:11], 0, v[2:3]
	global_store_dwordx4 v[10:11], v[6:9], off nt

; #define LAS __attribute__((address_space(3)))
; DI u32x4 pack8(const float* f) { u32x4 w; w.x = pk2(f[0], f[1]); w.y = pk2(f[2], f[3]); w.z = pk2(f[4], f[5]); w.w = pk2(f[6], f[7]); return w; }
; template <int MODE> DI void transpose_job(LAS unsigned char* lds, const float* src, int K, int N, bf16_t* dst, int bid, int nblk) {
;     ...
;         for (int q = 0; q < 2; ++q) { const int t = t0 + q * nblk; LAS float* tl = (LAS float*)(lds + q * 16640);
;             if (t < ntile) { const int k0 = (t / tn) * 64, n0 = (t % tn) * 64, n = tid >> 3, ko = (tid & 7) * 8;
;                 if (n0 + n < N) { float f[8];
; #pragma unroll
;                     for (int jq = 0; jq < 8; ++jq) f[jq] = tl[(ko + jq) * 65 + n];
;                     *(u32x4*)(dst + (size_t)rowmap<MODE>(n0 + n) * K + k0 + ko) = pack8(f); } } }
.LBB0_223:
	s_waitcnt lgkmcnt(0)
	s_barrier
	v_add_u32_e32 v2, s20, v15
	s_movk_i32 s20, 0x800
	v_cmp_gt_i32_e32 vcc, s20, v2
	s_and_saveexec_b64 s[20:21], vcc
	s_cbranch_execz .LBB0_225
	v_add_u32_e32 v8, v16, v18
	ds_read2_b32 v[4:5], v8 offset1:65
	ds_read2_b32 v[6:7], v8 offset0:130 offset1:195
	v_add_u32_e32 v10, 0x400, v8
	ds_read2_b32 v[8:9], v10 offset0:4 offset1:69
	ds_read2_b32 v[10:11], v10 offset0:134 offset1:199
	s_ashr_i32 s26, s31, 5
	s_lshl_b32 s26, s26, 6
	s_waitcnt lgkmcnt(3)
	v_cvt_pk_bf16_f32 v4, v4, v5
	s_waitcnt lgkmcnt(2)
	v_cvt_pk_bf16_f32 v5, v6, v7
	s_waitcnt lgkmcnt(1)
	v_cvt_pk_bf16_f32 v6, v8, v9
	v_mov_b64_e32 v[8:9], s[2:3]
	s_movk_i32 s27, 0x2c00
	v_mad_i64_i32 v[8:9], s[28:29], v2, s27, v[8:9]
	s_ashr_i32 s27, s26, 31
	v_lshl_add_u64 v[8:9], s[26:27], 1, v[8:9]
	v_lshlrev_b32_e32 v2, 1, v12
	s_waitcnt lgkmcnt(0)
	v_cvt_pk_bf16_f32 v7, v10, v11
	v_lshl_add_u64 v[8:9], v[8:9], 0, v[2:3]
	global_store_dwordx4 v[8:9], v[4:7], off nt
.LBB0_225:
	s_or_b64 exec, exec, s[20:21]
	s_andn2_b64 vcc, exec, s[22:23]
	s_cbranch_vccnz .LBB0_216
	s_ashr_i32 s20, s34, 31
	s_lshr_b32 s20, s20, 27
	s_add_i32 s22, s34, s20
	s_and_b32 s20, s22, 0x3ffffe0
	s_sub_i32 s20, s34, s20
	v_lshl_add_u32 v2, s20, 6, v15
	s_movk_i32 s20, 0x800
	v_cmp_gt_i32_e32 vcc, s20, v2
	s_and_saveexec_b64 s[20:21], vcc
	s_cbranch_execz .LBB0_215
	v_add_u32_e32 v10, v16, v18
	v_add_u32_e32 v4, 0x4000, v10
	v_add_u32_e32 v6, 0x4200, v10
	v_add_u32_e32 v8, 0x4400, v10
	ds_read2_b32 v[4:5], v4 offset0:64 offset1:129
	ds_read2_b32 v[6:7], v6 offset0:66 offset1:131
	ds_read2_b32 v[8:9], v8 offset0:68 offset1:133
	v_add_u32_e32 v10, 0x4600, v10
	ds_read2_b32 v[10:11], v10 offset0:70 offset1:135
	s_ashr_i32 s22, s22, 5
	s_lshl_b32 s22, s22, 6
	s_waitcnt lgkmcnt(3)
	v_cvt_pk_bf16_f32 v4, v4, v5
	s_waitcnt lgkmcnt(2)
	v_cvt_pk_bf16_f32 v5, v6, v7
	s_waitcnt lgkmcnt(1)
	v_cvt_pk_bf16_f32 v6, v8, v9
	v_mov_b64_e32 v[8:9], s[2:3]
	s_movk_i32 s23, 0x2c00
	v_mad_i64_i32 v[8:9], s[26:27], v2, s23, v[8:9]
	s_ashr_i32 s23, s22, 31
	v_lshl_add_u64 v[8:9], s[22:23], 1, v[8:9]
	v_lshlrev_b32_e32 v2, 1, v12
	s_waitcnt lgkmcnt(0)
	v_cvt_pk_bf16_f32 v7, v10, v11
	v_lshl_add_u64 v[8:9], v[8:9], 0, v[2:3]
	global_store_dwordx4 v[8:9], v[4:7], off nt
	s_branch .LBB0_215

; DI u32x4 pack8(const float* f) { u32x4 w; w.x = pk2(f[0], f[1]); w.y = pk2(f[2], f[3]); w.z = pk2(f[4], f[5]); w.w = pk2(f[6], f[7]); return w; }
; template <int MODE> DI void transpose_job(LAS unsigned char* lds, const float* src, int K, int N, bf16_t* dst, int bid, int nblk) {
;     ...
;             if (t < ntile) { const int k0 = (t / tn) * 64, n0 = (t % tn) * 64, n = tid >> 3, ko = (tid & 7) * 8;
;                 if (n0 + n < N) { float f[8];
; #pragma unroll
;                     for (int jq = 0; jq < 8; ++jq) f[jq] = tl[(ko + jq) * 65 + n];
;                     *(u32x4*)(dst + (size_t)rowmap<MODE>(n0 + n) * K + k0 + ko) = pack8(f); } } }
.LBB0_309:
	s_or_b64 exec, exec, s[22:23]
	v_ashrrev_i32_e32 v5, 31, v4
	s_lshl_b32 s22, s27, 6
	v_lshlrev_b64 v[4:5], 12, v[4:5]
	v_lshl_add_u64 v[4:5], s[94:95], 0, v[4:5]
	s_ashr_i32 s23, s22, 31
	v_lshl_add_u64 v[4:5], s[22:23], 1, v[4:5]
	v_lshlrev_b32_e32 v2, 1, v12
	s_waitcnt lgkmcnt(3)
	v_cvt_pk_bf16_f32 v6, v6, v7
	s_waitcnt lgkmcnt(2)
	v_cvt_pk_bf16_f32 v7, v8, v9
	s_waitcnt lgkmcnt(1)
	v_cvt_pk_bf16_f32 v8, v10, v11
	s_waitcnt lgkmcnt(0)
	v_cvt_pk_bf16_f32 v9, v14, v15
	v_lshl_add_u64 v[4:5], v[4:5], 0, v[2:3]
	global_store_dwordx4 v[4:5], v[6:9], off nt

; #define LAS __attribute__((address_space(3)))
; DI u32x4 pack8(const float* f) { u32x4 w; w.x = pk2(f[0], f[1]); w.y = pk2(f[2], f[3]); w.z = pk2(f[4], f[5]); w.w = pk2(f[6], f[7]); return w; }
; template <int MODE> DI void transpose_job(LAS unsigned char* lds, const float* src, int K, int N, bf16_t* dst, int bid, int nblk) {
;     ...
;         for (int q = 0; q < 2; ++q) { const int t = t0 + q * nblk; LAS float* tl = (LAS float*)(lds + q * 16640);
;             if (t < ntile) { const int k0 = (t / tn) * 64, n0 = (t % tn) * 64, n = tid >> 3, ko = (tid & 7) * 8;
;                 if (n0 + n < N) { float f[8];
; #pragma unroll
;                     for (int jq = 0; jq < 8; ++jq) f[jq] = tl[(ko + jq) * 65 + n];
;                     *(u32x4*)(dst + (size_t)rowmap<MODE>(n0 + n) * K + k0 + ko) = pack8(f); } } }
.LBB0_327:
	s_waitcnt lgkmcnt(0)
	s_barrier
	v_add_u32_e32 v4, s2, v15
	s_movk_i32 s2, 0x400
	v_cmp_gt_i32_e32 vcc, s2, v4
	s_and_saveexec_b64 s[2:3], vcc
	s_cbranch_execz .LBB0_329
	v_add_u32_e32 v2, v16, v18
	ds_read2_b32 v[6:7], v2 offset1:65
	ds_read2_b32 v[8:9], v2 offset0:130 offset1:195
	v_add_u32_e32 v2, 0x400, v2
	ds_read2_b32 v[10:11], v2 offset0:4 offset1:69
	ds_read2_b32 v[20:21], v2 offset0:134 offset1:199
	s_ashr_i32 s22, s27, 4
	v_ashrrev_i32_e32 v5, 31, v4
	s_lshl_b32 s22, s22, 6
	v_lshlrev_b64 v[4:5], 11, v[4:5]
	v_lshl_add_u64 v[4:5], s[60:61], 0, v[4:5]
	s_ashr_i32 s23, s22, 31
	v_lshl_add_u64 v[4:5], s[22:23], 1, v[4:5]
	v_lshlrev_b32_e32 v2, 1, v12
	s_waitcnt lgkmcnt(3)
	v_cvt_pk_bf16_f32 v6, v6, v7
	s_waitcnt lgkmcnt(2)
	v_cvt_pk_bf16_f32 v7, v8, v9
	s_waitcnt lgkmcnt(1)
	v_cvt_pk_bf16_f32 v8, v10, v11
	s_waitcnt lgkmcnt(0)
	v_cvt_pk_bf16_f32 v9, v20, v21
	v_lshl_add_u64 v[4:5], v[4:5], 0, v[2:3]
	global_store_dwordx4 v[4:5], v[6:9], off nt
.LBB0_329:
	s_or_b64 exec, exec, s[2:3]
	s_andn2_b64 vcc, exec, s[20:21]
	s_cbranch_vccnz .LBB0_320
	s_ashr_i32 s2, s28, 31
	s_lshr_b32 s2, s2, 28
	s_add_i32 s20, s28, s2
	s_and_b32 s2, s20, 0x3fffff0
	s_sub_i32 s2, s28, s2
	v_lshl_add_u32 v4, s2, 6, v15
	s_movk_i32 s2, 0x400
	v_cmp_gt_i32_e32 vcc, s2, v4
	s_and_saveexec_b64 s[2:3], vcc
	s_cbranch_execz .LBB0_319
	v_add_u32_e32 v2, v16, v18
	v_add_u32_e32 v5, 0x4000, v2
	ds_read2_b32 v[6:7], v5 offset0:64 offset1:129
	v_add_u32_e32 v5, 0x4200, v2
	ds_read2_b32 v[8:9], v5 offset0:66 offset1:131
	v_add_u32_e32 v5, 0x4400, v2
	v_add_u32_e32 v2, 0x4600, v2
	ds_read2_b32 v[10:11], v5 offset0:68 offset1:133
	ds_read2_b32 v[20:21], v2 offset0:70 offset1:135
	s_ashr_i32 s20, s20, 4
	v_ashrrev_i32_e32 v5, 31, v4
	s_lshl_b32 s20, s20, 6
	v_lshlrev_b64 v[4:5], 11, v[4:5]
	v_lshl_add_u64 v[4:5], s[60:61], 0, v[4:5]
	s_ashr_i32 s21, s20, 31
	v_lshl_add_u64 v[4:5], s[20:21], 1, v[4:5]
	v_lshlrev_b32_e32 v2, 1, v12
	s_waitcnt lgkmcnt(3)
	v_cvt_pk_bf16_f32 v6, v6, v7
	s_waitcnt lgkmcnt(2)
	v_cvt_pk_bf16_f32 v7, v8, v9
	s_waitcnt lgkmcnt(1)
	v_cvt_pk_bf16_f32 v8, v10, v11
	s_waitcnt lgkmcnt(0)
	v_cvt_pk_bf16_f32 v9, v20, v21
	v_lshl_add_u64 v[4:5], v[4:5], 0, v[2:3]
	global_store_dwordx4 v[4:5], v[6:9], off nt
	s_branch .LBB0_319

; #define LAS __attribute__((address_space(3)))
; DI u32x4 pack8(const float* f) { u32x4 w; w.x = pk2(f[0], f[1]); w.y = pk2(f[2], f[3]); w.z = pk2(f[4], f[5]); w.w = pk2(f[6], f[7]); return w; }
; template <int MODE> DI void transpose_job(LAS unsigned char* lds, const float* src, int K, int N, bf16_t* dst, int bid, int nblk) {
;     ...
;         for (int q = 0; q < 2; ++q) { const int t = t0 + q * nblk; LAS float* tl = (LAS float*)(lds + q * 16640);
;             if (t < ntile) { const int k0 = (t / tn) * 64, n0 = (t % tn) * 64, n = tid >> 3, ko = (tid & 7) * 8;
;                 if (n0 + n < N) { float f[8];
; #pragma unroll
;                     for (int jq = 0; jq < 8; ++jq) f[jq] = tl[(ko + jq) * 65 + n];
;                     *(u32x4*)(dst + (size_t)rowmap<MODE>(n0 + n) * K + k0 + ko) = pack8(f); } } }
.LBB0_342:
	s_waitcnt lgkmcnt(0)
	s_barrier
	v_add_u32_e32 v4, s2, v15
	s_movk_i32 s2, 0x800
	v_cmp_gt_i32_e32 vcc, s2, v4
	s_and_saveexec_b64 s[2:3], vcc
	s_cbranch_execz .LBB0_344
	v_add_u32_e32 v2, v16, v18
	ds_read2_b32 v[6:7], v2 offset1:65
	ds_read2_b32 v[8:9], v2 offset0:130 offset1:195
	v_add_u32_e32 v2, 0x400, v2
	ds_read2_b32 v[10:11], v2 offset0:4 offset1:69
	ds_read2_b32 v[20:21], v2 offset0:134 offset1:199
	s_ashr_i32 s22, s27, 5
	v_ashrrev_i32_e32 v5, 31, v4
	s_lshl_b32 s22, s22, 6
	v_lshlrev_b64 v[4:5], 11, v[4:5]
	v_lshl_add_u64 v[4:5], s[64:65], 0, v[4:5]
	s_ashr_i32 s23, s22, 31
	v_lshl_add_u64 v[4:5], s[22:23], 1, v[4:5]
	v_lshlrev_b32_e32 v2, 1, v12
	s_waitcnt lgkmcnt(3)
	v_cvt_pk_bf16_f32 v6, v6, v7
	s_waitcnt lgkmcnt(2)
	v_cvt_pk_bf16_f32 v7, v8, v9
	s_waitcnt lgkmcnt(1)
	v_cvt_pk_bf16_f32 v8, v10, v11
	s_waitcnt lgkmcnt(0)
	v_cvt_pk_bf16_f32 v9, v20, v21
	v_lshl_add_u64 v[4:5], v[4:5], 0, v[2:3]
	global_store_dwordx4 v[4:5], v[6:9], off nt
.LBB0_344:
	s_or_b64 exec, exec, s[2:3]
	s_andn2_b64 vcc, exec, s[20:21]
	s_cbranch_vccnz .LBB0_335
	s_ashr_i32 s2, s28, 31
	s_lshr_b32 s2, s2, 27
	s_add_i32 s20, s28, s2
	s_and_b32 s2, s20, 0x3ffffe0
	s_sub_i32 s2, s28, s2
	v_lshl_add_u32 v4, s2, 6, v15
	s_movk_i32 s2, 0x800
	v_cmp_gt_i32_e32 vcc, s2, v4
	s_and_saveexec_b64 s[2:3], vcc
	s_cbranch_execz .LBB0_334
	v_add_u32_e32 v2, v16, v18
	v_add_u32_e32 v5, 0x4000, v2
	ds_read2_b32 v[6:7], v5 offset0:64 offset1:129
	v_add_u32_e32 v5, 0x4200, v2
	ds_read2_b32 v[8:9], v5 offset0:66 offset1:131
	v_add_u32_e32 v5, 0x4400, v2
	v_add_u32_e32 v2, 0x4600, v2
	ds_read2_b32 v[10:11], v5 offset0:68 offset1:133
	ds_read2_b32 v[20:21], v2 offset0:70 offset1:135
	s_ashr_i32 s20, s20, 5
	v_ashrrev_i32_e32 v5, 31, v4
	s_lshl_b32 s20, s20, 6
	v_lshlrev_b64 v[4:5], 11, v[4:5]
	v_lshl_add_u64 v[4:5], s[64:65], 0, v[4:5]
	s_ashr_i32 s21, s20, 31
	v_lshl_add_u64 v[4:5], s[20:21], 1, v[4:5]
	v_lshlrev_b32_e32 v2, 1, v12
	s_waitcnt lgkmcnt(3)
	v_cvt_pk_bf16_f32 v6, v6, v7
	s_waitcnt lgkmcnt(2)
	v_cvt_pk_bf16_f32 v7, v8, v9
	s_waitcnt lgkmcnt(1)
	v_cvt_pk_bf16_f32 v8, v10, v11
	s_waitcnt lgkmcnt(0)
	v_cvt_pk_bf16_f32 v9, v20, v21
	v_lshl_add_u64 v[4:5], v[4:5], 0, v[2:3]
	global_store_dwordx4 v[4:5], v[6:9], off nt
	s_branch .LBB0_334

; DI int TID() { int t = __builtin_amdgcn_workitem_id_x(); asm volatile("" : "+v"(t)); return t; }
; DI void phase_weights_a(LAS unsigned char* lds, PP p, int l, int bid, int nblk) {
;     ...
;     { u32x4* z = (u32x4*)(ws + O_WIN + (size_t)9232 * 2048 * 2); const int nz = 240 * 2048 * 2 / 16;
;       for (int i = bid * NTHR + TID(); i < nz; i += nblk * NTHR) z[i] = (u32x4){0u, 0u, 0u, 0u}; }
.LBB0_349:
	v_add_u32_e32 v0, s22, v0
	v_cmp_lt_i32_e32 vcc, s23, v0
	global_store_dwordx4 v[4:5], v[240:243], off nt
	s_or_b64 s[20:21], vcc, s[20:21]
	v_lshl_add_u64 v[4:5], v[4:5], 0, s[24:25]
	s_andn2_b64 exec, exec, s[20:21]
	s_cbranch_execnz .LBB0_349

; DI u32x4 pack8(const float* f) { u32x4 w; w.x = pk2(f[0], f[1]); w.y = pk2(f[2], f[3]); w.z = pk2(f[4], f[5]); w.w = pk2(f[6], f[7]); return w; }
; template <int MODE> DI void transpose_job(LAS unsigned char* lds, const float* src, int K, int N, bf16_t* dst, int bid, int nblk) {
;     ...
;             if (t < ntile) { const int k0 = (t / tn) * 64, n0 = (t % tn) * 64, n = tid >> 3, ko = (tid & 7) * 8;
;                 if (n0 + n < N) { float f[8];
; #pragma unroll
;                     for (int jq = 0; jq < 8; ++jq) f[jq] = tl[(ko + jq) * 65 + n];
;                     *(u32x4*)(dst + (size_t)rowmap<MODE>(n0 + n) * K + k0 + ko) = pack8(f); } } }
.LBB0_1344:
	s_or_b64 exec, exec, s[20:21]
	v_ashrrev_i32_e32 v5, 31, v4
	s_lshl_b32 s20, s25, 6
	v_lshlrev_b64 v[4:5], 12, v[4:5]
	v_lshl_add_u64 v[4:5], s[94:95], 0, v[4:5]
	s_ashr_i32 s21, s20, 31
	v_lshl_add_u64 v[4:5], s[20:21], 1, v[4:5]
	v_lshlrev_b32_e32 v2, 1, v12
	s_waitcnt lgkmcnt(3)
	v_cvt_pk_bf16_f32 v6, v6, v7
	s_waitcnt lgkmcnt(2)
	v_cvt_pk_bf16_f32 v7, v8, v9
	s_waitcnt lgkmcnt(1)
	v_cvt_pk_bf16_f32 v8, v10, v11
	s_waitcnt lgkmcnt(0)
	v_cvt_pk_bf16_f32 v9, v14, v15
	v_lshl_add_u64 v[4:5], v[4:5], 0, v[2:3]
	global_store_dwordx4 v[4:5], v[6:9], off nt

; #define LAS __attribute__((address_space(3)))
; DI u32x4 pack8(const float* f) { u32x4 w; w.x = pk2(f[0], f[1]); w.y = pk2(f[2], f[3]); w.z = pk2(f[4], f[5]); w.w = pk2(f[6], f[7]); return w; }
; template <int MODE> DI void transpose_job(LAS unsigned char* lds, const float* src, int K, int N, bf16_t* dst, int bid, int nblk) {
;     ...
;         for (int q = 0; q < 2; ++q) { const int t = t0 + q * nblk; LAS float* tl = (LAS float*)(lds + q * 16640);
;             if (t < ntile) { const int k0 = (t / tn) * 64, n0 = (t % tn) * 64, n = tid >> 3, ko = (tid & 7) * 8;
;                 if (n0 + n < N) { float f[8];
; #pragma unroll
;                     for (int jq = 0; jq < 8; ++jq) f[jq] = tl[(ko + jq) * 65 + n];
;                     *(u32x4*)(dst + (size_t)rowmap<MODE>(n0 + n) * K + k0 + ko) = pack8(f); } } }
.LBB0_1362:
	s_waitcnt lgkmcnt(0)
	s_barrier
	v_add_u32_e32 v4, s4, v15
	v_cmp_gt_i32_e32 vcc, s30, v4
	s_and_saveexec_b64 s[4:5], vcc
	s_cbranch_execz .LBB0_1364
	v_add_u32_e32 v2, v16, v18
	ds_read2_b32 v[6:7], v2 offset1:65
	ds_read2_b32 v[8:9], v2 offset0:130 offset1:195
	v_add_u32_e32 v2, 0x400, v2
	ds_read2_b32 v[10:11], v2 offset0:4 offset1:69
	ds_read2_b32 v[20:21], v2 offset0:134 offset1:199
	s_ashr_i32 s22, s27, 4
	v_ashrrev_i32_e32 v5, 31, v4
	s_lshl_b32 s22, s22, 6
	v_lshlrev_b64 v[4:5], 11, v[4:5]
	v_lshl_add_u64 v[4:5], s[2:3], 0, v[4:5]
	s_ashr_i32 s23, s22, 31
	v_lshl_add_u64 v[4:5], s[22:23], 1, v[4:5]
	v_lshlrev_b32_e32 v2, 1, v12
	s_waitcnt lgkmcnt(3)
	v_cvt_pk_bf16_f32 v6, v6, v7
	s_waitcnt lgkmcnt(2)
	v_cvt_pk_bf16_f32 v7, v8, v9
	s_waitcnt lgkmcnt(1)
	v_cvt_pk_bf16_f32 v8, v10, v11
	s_waitcnt lgkmcnt(0)
	v_cvt_pk_bf16_f32 v9, v20, v21
	v_lshl_add_u64 v[4:5], v[4:5], 0, v[2:3]
	global_store_dwordx4 v[4:5], v[6:9], off nt
.LBB0_1364:
	s_or_b64 exec, exec, s[4:5]
	s_andn2_b64 vcc, exec, s[20:21]
	s_cbranch_vccnz .LBB0_1355
	s_ashr_i32 s4, s26, 31
	s_lshr_b32 s4, s4, 28
	s_add_i32 s20, s26, s4
	s_and_b32 s4, s20, 0x3fffff0
	s_sub_i32 s4, s26, s4
	v_lshl_add_u32 v4, s4, 6, v15
	v_cmp_gt_i32_e32 vcc, s30, v4
	s_and_saveexec_b64 s[4:5], vcc
	s_cbranch_execz .LBB0_1354
	v_add_u32_e32 v2, v16, v18
	v_add_u32_e32 v5, 0x4000, v2
	ds_read2_b32 v[6:7], v5 offset0:64 offset1:129
	v_add_u32_e32 v5, 0x4200, v2
	ds_read2_b32 v[8:9], v5 offset0:66 offset1:131
	v_add_u32_e32 v5, 0x4400, v2
	v_add_u32_e32 v2, 0x4600, v2
	ds_read2_b32 v[10:11], v5 offset0:68 offset1:133
	ds_read2_b32 v[20:21], v2 offset0:70 offset1:135
	s_ashr_i32 s20, s20, 4
	v_ashrrev_i32_e32 v5, 31, v4
	s_lshl_b32 s20, s20, 6
	v_lshlrev_b64 v[4:5], 11, v[4:5]
	v_lshl_add_u64 v[4:5], s[2:3], 0, v[4:5]
	s_ashr_i32 s21, s20, 31
	v_lshl_add_u64 v[4:5], s[20:21], 1, v[4:5]
	v_lshlrev_b32_e32 v2, 1, v12
	s_waitcnt lgkmcnt(3)
	v_cvt_pk_bf16_f32 v6, v6, v7
	s_waitcnt lgkmcnt(2)
	v_cvt_pk_bf16_f32 v7, v8, v9
	s_waitcnt lgkmcnt(1)
	v_cvt_pk_bf16_f32 v8, v10, v11
	s_waitcnt lgkmcnt(0)
	v_cvt_pk_bf16_f32 v9, v20, v21
	v_lshl_add_u64 v[4:5], v[4:5], 0, v[2:3]
	global_store_dwordx4 v[4:5], v[6:9], off nt
	s_branch .LBB0_1354

; #define LAS __attribute__((address_space(3)))
; DI u32x4 pack8(const float* f) { u32x4 w; w.x = pk2(f[0], f[1]); w.y = pk2(f[2], f[3]); w.z = pk2(f[4], f[5]); w.w = pk2(f[6], f[7]); return w; }
; template <int MODE> DI void transpose_job(LAS unsigned char* lds, const float* src, int K, int N, bf16_t* dst, int bid, int nblk) {
;     ...
;         for (int q = 0; q < 2; ++q) { const int t = t0 + q * nblk; LAS float* tl = (LAS float*)(lds + q * 16640);
;             if (t < ntile) { const int k0 = (t / tn) * 64, n0 = (t % tn) * 64, n = tid >> 3, ko = (tid & 7) * 8;
;                 if (n0 + n < N) { float f[8];
; #pragma unroll
;                     for (int jq = 0; jq < 8; ++jq) f[jq] = tl[(ko + jq) * 65 + n];
;                     *(u32x4*)(dst + (size_t)rowmap<MODE>(n0 + n) * K + k0 + ko) = pack8(f); } } }
.LBB0_1377:
	s_waitcnt lgkmcnt(0)
	s_barrier
	v_add_u32_e32 v4, s2, v15
	v_cmp_gt_i32_e32 vcc, s31, v4
	s_and_saveexec_b64 s[2:3], vcc
	s_cbranch_execz .LBB0_1379
	v_add_u32_e32 v2, v16, v18
	ds_read2_b32 v[6:7], v2 offset1:65
	ds_read2_b32 v[8:9], v2 offset0:130 offset1:195
	v_add_u32_e32 v2, 0x400, v2
	ds_read2_b32 v[10:11], v2 offset0:4 offset1:69
	ds_read2_b32 v[20:21], v2 offset0:134 offset1:199
	s_ashr_i32 s20, s25, 5
	v_ashrrev_i32_e32 v5, 31, v4
	s_lshl_b32 s20, s20, 6
	v_lshlrev_b64 v[4:5], 11, v[4:5]
	v_lshl_add_u64 v[4:5], s[0:1], 0, v[4:5]
	s_ashr_i32 s21, s20, 31
	v_lshl_add_u64 v[4:5], s[20:21], 1, v[4:5]
	v_lshlrev_b32_e32 v2, 1, v12
	s_waitcnt lgkmcnt(3)
	v_cvt_pk_bf16_f32 v6, v6, v7
	s_waitcnt lgkmcnt(2)
	v_cvt_pk_bf16_f32 v7, v8, v9
	s_waitcnt lgkmcnt(1)
	v_cvt_pk_bf16_f32 v8, v10, v11
	s_waitcnt lgkmcnt(0)
	v_cvt_pk_bf16_f32 v9, v20, v21
	v_lshl_add_u64 v[4:5], v[4:5], 0, v[2:3]
	global_store_dwordx4 v[4:5], v[6:9], off nt
.LBB0_1379:
	s_or_b64 exec, exec, s[2:3]
	s_andn2_b64 vcc, exec, s[4:5]
	s_cbranch_vccnz .LBB0_1370
	s_ashr_i32 s2, s24, 31
	s_lshr_b32 s2, s2, 27
	s_add_i32 s4, s24, s2
	s_and_b32 s2, s4, 0x3ffffe0
	s_sub_i32 s2, s24, s2
	v_lshl_add_u32 v4, s2, 6, v15
	v_cmp_gt_i32_e32 vcc, s31, v4
	s_and_saveexec_b64 s[2:3], vcc
	s_cbranch_execz .LBB0_1369
	v_add_u32_e32 v2, v16, v18
	v_add_u32_e32 v5, 0x4000, v2
	ds_read2_b32 v[6:7], v5 offset0:64 offset1:129
	v_add_u32_e32 v5, 0x4200, v2
	ds_read2_b32 v[8:9], v5 offset0:66 offset1:131
	v_add_u32_e32 v5, 0x4400, v2
	v_add_u32_e32 v2, 0x4600, v2
	ds_read2_b32 v[10:11], v5 offset0:68 offset1:133
	ds_read2_b32 v[20:21], v2 offset0:70 offset1:135
	s_ashr_i32 s4, s4, 5
	v_ashrrev_i32_e32 v5, 31, v4
	s_lshl_b32 s4, s4, 6
	v_lshlrev_b64 v[4:5], 11, v[4:5]
	v_lshl_add_u64 v[4:5], s[0:1], 0, v[4:5]
	s_ashr_i32 s5, s4, 31
	v_lshl_add_u64 v[4:5], s[4:5], 1, v[4:5]
	v_lshlrev_b32_e32 v2, 1, v12
	s_waitcnt lgkmcnt(3)
	v_cvt_pk_bf16_f32 v6, v6, v7
	s_waitcnt lgkmcnt(2)
	v_cvt_pk_bf16_f32 v7, v8, v9
	s_waitcnt lgkmcnt(1)
	v_cvt_pk_bf16_f32 v8, v10, v11
	s_waitcnt lgkmcnt(0)
	v_cvt_pk_bf16_f32 v9, v20, v21
	v_lshl_add_u64 v[4:5], v[4:5], 0, v[2:3]
	global_store_dwordx4 v[4:5], v[6:9], off nt
	s_branch .LBB0_1369

; DI int TID() { int t = __builtin_amdgcn_workitem_id_x(); asm volatile("" : "+v"(t)); return t; }
; DI void phase_weights_a(LAS unsigned char* lds, PP p, int l, int bid, int nblk) {
;     ...
;     { u32x4* z = (u32x4*)(ws + O_WIN + (size_t)9232 * 2048 * 2); const int nz = 240 * 2048 * 2 / 16;
;       for (int i = bid * NTHR + TID(); i < nz; i += nblk * NTHR) z[i] = (u32x4){0u, 0u, 0u, 0u}; }
.LBB0_1384:
	v_add_u32_e32 v0, s68, v0
	v_cmp_lt_i32_e32 vcc, s4, v0
	global_store_dwordx4 v[4:5], v[240:243], off nt
	s_or_b64 s[2:3], vcc, s[2:3]
	v_lshl_add_u64 v[4:5], v[4:5], 0, s[34:35]
	s_andn2_b64 exec, exec, s[2:3]
	s_cbranch_execnz .LBB0_1384
